# grid barrier: the globally last XCD leader bumps the generation words of all XCDs itself (one polling hop less for the other XCDs' waiters)
# speedup vs baseline: 1.0057x; 1.0057x over previous
.LBB0_118:
	s_or_b64 exec, exec, s[8:9]
	s_and_saveexec_b64 s[8:9], s[12:13]
	s_cbranch_execz .LBB0_120
	v_mov_b32_e32 v4, 1
	global_atomic_add v[2:3], v4, off
	v_mov_b32_e32 v2, 0x2400
	global_atomic_add v2, v4, s[68:69]
	v_add_u32_e32 v2, 0x100, v2
	global_atomic_add v2, v4, s[68:69]
	v_add_u32_e32 v2, 0x100, v2
	global_atomic_add v2, v4, s[68:69]
	v_add_u32_e32 v2, 0x100, v2
	global_atomic_add v2, v4, s[68:69]
	v_add_u32_e32 v2, 0x100, v2
	global_atomic_add v2, v4, s[68:69]
	v_add_u32_e32 v2, 0x100, v2
	global_atomic_add v2, v4, s[68:69]
	v_add_u32_e32 v2, 0x100, v2
	global_atomic_add v2, v4, s[68:69]
	v_add_u32_e32 v2, 0x100, v2
	global_atomic_add v2, v4, s[68:69]
	v_add_u32_e32 v2, 0x100, v2
	global_atomic_add v2, v4, s[68:69]
	v_add_u32_e32 v2, 0x100, v2
	global_atomic_add v2, v4, s[68:69]
	v_add_u32_e32 v2, 0x100, v2
	global_atomic_add v2, v4, s[68:69]
	v_add_u32_e32 v2, 0x100, v2
	global_atomic_add v2, v4, s[68:69]
	v_add_u32_e32 v2, 0x100, v2
	global_atomic_add v2, v4, s[68:69]
	v_add_u32_e32 v2, 0x100, v2
	global_atomic_add v2, v4, s[68:69]
	v_add_u32_e32 v2, 0x100, v2
	global_atomic_add v2, v4, s[68:69]
	v_add_u32_e32 v2, 0x100, v2
	global_atomic_add v2, v4, s[68:69]
.LBB0_120:
	s_or_b64 exec, exec, s[8:9]
	s_mov_b64 s[8:9], exec
	v_mbcnt_lo_u32_b32 v2, s8, 0
	v_mbcnt_hi_u32_b32 v2, s9, v2
	v_cmp_eq_u32_e32 vcc, 0, v2
	s_waitcnt vmcnt(0)
	s_and_saveexec_b64 s[10:11], vcc
	s_cbranch_execz .LBB0_122
	s_bcnt1_i32_b64 s3, s[8:9]
	v_mov_b32_e32 v2, 0x2000
	v_mov_b32_e32 v3, s3
.LBB0_122:
	s_or_b64 exec, exec, s[10:11]
	s_waitcnt vmcnt(0)

.LBB0_198:
	s_or_b64 exec, exec, s[8:9]
	s_mov_b64 s[8:9], exec
	v_mbcnt_lo_u32_b32 v2, s8, 0
	v_mbcnt_hi_u32_b32 v2, s9, v2
	v_cmp_eq_u32_e32 vcc, 0, v2
	s_waitcnt vmcnt(0)
	s_and_saveexec_b64 s[10:11], vcc
	s_cbranch_execz .LBB0_200
	s_bcnt1_i32_b64 s3, s[8:9]
	v_mov_b32_e32 v2, 0x2000
	v_mov_b32_e32 v3, s3
.LBB0_200:
	s_or_b64 exec, exec, s[10:11]
	s_waitcnt vmcnt(0)

.LBB0_446:
	s_or_b64 exec, exec, s[6:7]
	s_and_saveexec_b64 s[6:7], s[10:11]
	s_cbranch_execz .LBB0_448
	v_mov_b32_e32 v4, 1
	global_atomic_add v[2:3], v4, off
	v_mov_b32_e32 v2, 0x2400
	global_atomic_add v2, v4, s[68:69]
	v_add_u32_e32 v2, 0x100, v2
	global_atomic_add v2, v4, s[68:69]
	v_add_u32_e32 v2, 0x100, v2
	global_atomic_add v2, v4, s[68:69]
	v_add_u32_e32 v2, 0x100, v2
	global_atomic_add v2, v4, s[68:69]
	v_add_u32_e32 v2, 0x100, v2
	global_atomic_add v2, v4, s[68:69]
	v_add_u32_e32 v2, 0x100, v2
	global_atomic_add v2, v4, s[68:69]
	v_add_u32_e32 v2, 0x100, v2
	global_atomic_add v2, v4, s[68:69]
	v_add_u32_e32 v2, 0x100, v2
	global_atomic_add v2, v4, s[68:69]
	v_add_u32_e32 v2, 0x100, v2
	global_atomic_add v2, v4, s[68:69]
	v_add_u32_e32 v2, 0x100, v2
	global_atomic_add v2, v4, s[68:69]
	v_add_u32_e32 v2, 0x100, v2
	global_atomic_add v2, v4, s[68:69]
	v_add_u32_e32 v2, 0x100, v2
	global_atomic_add v2, v4, s[68:69]
	v_add_u32_e32 v2, 0x100, v2
	global_atomic_add v2, v4, s[68:69]
	v_add_u32_e32 v2, 0x100, v2
	global_atomic_add v2, v4, s[68:69]
	v_add_u32_e32 v2, 0x100, v2
	global_atomic_add v2, v4, s[68:69]
	v_add_u32_e32 v2, 0x100, v2
	global_atomic_add v2, v4, s[68:69]
.LBB0_448:
	s_or_b64 exec, exec, s[6:7]
	s_mov_b64 s[6:7], exec
	v_mbcnt_lo_u32_b32 v2, s6, 0
	v_mbcnt_hi_u32_b32 v2, s7, v2
	v_cmp_eq_u32_e32 vcc, 0, v2
	s_waitcnt vmcnt(0)
	s_and_saveexec_b64 s[8:9], vcc
	s_cbranch_execz .LBB0_450
	s_bcnt1_i32_b64 s3, s[6:7]
	v_mov_b32_e32 v2, 0x2000
	v_mov_b32_e32 v3, s3
.LBB0_450:
	s_or_b64 exec, exec, s[8:9]
	s_waitcnt vmcnt(0)

.LBB0_617:
	s_or_b64 exec, exec, s[8:9]
	s_and_saveexec_b64 s[8:9], s[12:13]
	s_cbranch_execz .LBB0_619
	v_mov_b32_e32 v1, 1
	global_atomic_add v[2:3], v1, off
	v_mov_b32_e32 v2, 0x2400
	global_atomic_add v2, v1, s[68:69]
	v_add_u32_e32 v2, 0x100, v2
	global_atomic_add v2, v1, s[68:69]
	v_add_u32_e32 v2, 0x100, v2
	global_atomic_add v2, v1, s[68:69]
	v_add_u32_e32 v2, 0x100, v2
	global_atomic_add v2, v1, s[68:69]
	v_add_u32_e32 v2, 0x100, v2
	global_atomic_add v2, v1, s[68:69]
	v_add_u32_e32 v2, 0x100, v2
	global_atomic_add v2, v1, s[68:69]
	v_add_u32_e32 v2, 0x100, v2
	global_atomic_add v2, v1, s[68:69]
	v_add_u32_e32 v2, 0x100, v2
	global_atomic_add v2, v1, s[68:69]
	v_add_u32_e32 v2, 0x100, v2
	global_atomic_add v2, v1, s[68:69]
	v_add_u32_e32 v2, 0x100, v2
	global_atomic_add v2, v1, s[68:69]
	v_add_u32_e32 v2, 0x100, v2
	global_atomic_add v2, v1, s[68:69]
	v_add_u32_e32 v2, 0x100, v2
	global_atomic_add v2, v1, s[68:69]
	v_add_u32_e32 v2, 0x100, v2
	global_atomic_add v2, v1, s[68:69]
	v_add_u32_e32 v2, 0x100, v2
	global_atomic_add v2, v1, s[68:69]
	v_add_u32_e32 v2, 0x100, v2
	global_atomic_add v2, v1, s[68:69]
	v_add_u32_e32 v2, 0x100, v2
	global_atomic_add v2, v1, s[68:69]
.LBB0_619:
	s_or_b64 exec, exec, s[8:9]
	s_mov_b64 s[8:9], exec
	v_mbcnt_lo_u32_b32 v1, s8, 0
	v_mbcnt_hi_u32_b32 v1, s9, v1
	v_cmp_eq_u32_e32 vcc, 0, v1
	s_waitcnt vmcnt(0)
	s_and_saveexec_b64 s[10:11], vcc
	s_cbranch_execz .LBB0_621
	s_bcnt1_i32_b64 s3, s[8:9]
	v_mov_b32_e32 v1, 0x2000
	v_mov_b32_e32 v2, s3
.LBB0_621:
	s_or_b64 exec, exec, s[10:11]
	s_waitcnt vmcnt(0)

.LBB0_692:
	s_or_b64 exec, exec, s[10:11]
	s_and_saveexec_b64 s[10:11], s[14:15]
	s_cbranch_execz .LBB0_694
	v_mov_b32_e32 v1, 1
	global_atomic_add v[2:3], v1, off
	v_mov_b32_e32 v2, 0x2400
	global_atomic_add v2, v1, s[68:69]
	v_add_u32_e32 v2, 0x100, v2
	global_atomic_add v2, v1, s[68:69]
	v_add_u32_e32 v2, 0x100, v2
	global_atomic_add v2, v1, s[68:69]
	v_add_u32_e32 v2, 0x100, v2
	global_atomic_add v2, v1, s[68:69]
	v_add_u32_e32 v2, 0x100, v2
	global_atomic_add v2, v1, s[68:69]
	v_add_u32_e32 v2, 0x100, v2
	global_atomic_add v2, v1, s[68:69]
	v_add_u32_e32 v2, 0x100, v2
	global_atomic_add v2, v1, s[68:69]
	v_add_u32_e32 v2, 0x100, v2
	global_atomic_add v2, v1, s[68:69]
	v_add_u32_e32 v2, 0x100, v2
	global_atomic_add v2, v1, s[68:69]
	v_add_u32_e32 v2, 0x100, v2
	global_atomic_add v2, v1, s[68:69]
	v_add_u32_e32 v2, 0x100, v2
	global_atomic_add v2, v1, s[68:69]
	v_add_u32_e32 v2, 0x100, v2
	global_atomic_add v2, v1, s[68:69]
	v_add_u32_e32 v2, 0x100, v2
	global_atomic_add v2, v1, s[68:69]
	v_add_u32_e32 v2, 0x100, v2
	global_atomic_add v2, v1, s[68:69]
	v_add_u32_e32 v2, 0x100, v2
	global_atomic_add v2, v1, s[68:69]
	v_add_u32_e32 v2, 0x100, v2
	global_atomic_add v2, v1, s[68:69]
.LBB0_694:
	s_or_b64 exec, exec, s[10:11]
	s_mov_b64 s[10:11], exec
	v_mbcnt_lo_u32_b32 v1, s10, 0
	v_mbcnt_hi_u32_b32 v1, s11, v1
	v_cmp_eq_u32_e32 vcc, 0, v1
	s_waitcnt vmcnt(0)
	s_and_saveexec_b64 s[12:13], vcc
	s_cbranch_execz .LBB0_696
	s_bcnt1_i32_b64 s3, s[10:11]
	v_mov_b32_e32 v1, 0x2000
	v_mov_b32_e32 v2, s3
.LBB0_696:
	s_or_b64 exec, exec, s[12:13]
	s_waitcnt vmcnt(0)

.LBB0_788:
	s_or_b64 exec, exec, s[10:11]
	s_mov_b64 s[10:11], exec
	v_mbcnt_lo_u32_b32 v1, s10, 0
	v_mbcnt_hi_u32_b32 v1, s11, v1
	v_cmp_eq_u32_e32 vcc, 0, v1
	s_waitcnt vmcnt(0)
	s_and_saveexec_b64 s[12:13], vcc
	s_cbranch_execz .LBB0_790
	s_bcnt1_i32_b64 s3, s[10:11]
	v_mov_b32_e32 v1, 0x2000
	v_mov_b32_e32 v2, s3
.LBB0_790:
	s_or_b64 exec, exec, s[12:13]
	s_waitcnt vmcnt(0)

.LBB0_871:
	s_or_b64 exec, exec, s[10:11]
	s_and_saveexec_b64 s[10:11], s[14:15]
	s_cbranch_execz .LBB0_873
	v_mov_b32_e32 v2, 1
	global_atomic_add v[0:1], v2, off
	v_mov_b32_e32 v0, 0x2400
	global_atomic_add v0, v2, s[68:69]
	v_add_u32_e32 v0, 0x100, v0
	global_atomic_add v0, v2, s[68:69]
	v_add_u32_e32 v0, 0x100, v0
	global_atomic_add v0, v2, s[68:69]
	v_add_u32_e32 v0, 0x100, v0
	global_atomic_add v0, v2, s[68:69]
	v_add_u32_e32 v0, 0x100, v0
	global_atomic_add v0, v2, s[68:69]
	v_add_u32_e32 v0, 0x100, v0
	global_atomic_add v0, v2, s[68:69]
	v_add_u32_e32 v0, 0x100, v0
	global_atomic_add v0, v2, s[68:69]
	v_add_u32_e32 v0, 0x100, v0
	global_atomic_add v0, v2, s[68:69]
	v_add_u32_e32 v0, 0x100, v0
	global_atomic_add v0, v2, s[68:69]
	v_add_u32_e32 v0, 0x100, v0
	global_atomic_add v0, v2, s[68:69]
	v_add_u32_e32 v0, 0x100, v0
	global_atomic_add v0, v2, s[68:69]
	v_add_u32_e32 v0, 0x100, v0
	global_atomic_add v0, v2, s[68:69]
	v_add_u32_e32 v0, 0x100, v0
	global_atomic_add v0, v2, s[68:69]
	v_add_u32_e32 v0, 0x100, v0
	global_atomic_add v0, v2, s[68:69]
	v_add_u32_e32 v0, 0x100, v0
	global_atomic_add v0, v2, s[68:69]
	v_add_u32_e32 v0, 0x100, v0
	global_atomic_add v0, v2, s[68:69]
.LBB0_873:
	s_or_b64 exec, exec, s[10:11]
	s_mov_b64 s[10:11], exec
	v_mbcnt_lo_u32_b32 v0, s10, 0
	v_mbcnt_hi_u32_b32 v0, s11, v0
	v_cmp_eq_u32_e32 vcc, 0, v0
	s_waitcnt vmcnt(0)
	s_and_saveexec_b64 s[12:13], vcc
	s_cbranch_execz .LBB0_875
	s_bcnt1_i32_b64 s3, s[10:11]
	v_mov_b32_e32 v0, 0x2000
	v_mov_b32_e32 v1, s3
.LBB0_875:
	s_or_b64 exec, exec, s[12:13]
	s_waitcnt vmcnt(0)
